# A/B on final loop structure: static priority raise for waves 4-7 switched off (same byte layout)
# speedup vs baseline: 1.0095x; 1.0010x over previous
.LBB0_406:
	s_lshl_b32 s2, s6, 4
	v_readlane_b32 s3, v254, 17
	s_add_i32 s2, s3, s2
	s_ashr_i32 s4, s2, 3
	v_mbcnt_lo_u32_b32 v9, -1, 0
	v_mbcnt_hi_u32_b32 v9, -1, v9
	s_ashr_i32 s5, s4, 31
	v_ashrrev_i32_e32 v0, 3, v9
	v_add_u32_e32 v1, s36, v0
	s_lshl_b64 s[2:3], s[4:5], 12
	v_lshrrev_b32_e32 v1, 1, v1
	v_xor_b32_e32 v1, v1, v9
	s_add_i32 s5, s2, s36
	v_lshlrev_b32_e32 v1, 3, v1
	v_add_lshl_u32 v11, s5, v0, 10
	v_readlane_b32 s5, v254, 4
	v_and_b32_e32 v10, 56, v1
	v_ashrrev_i32_e32 v1, 4, v9
	s_add_i32 s5, s5, s2
	v_add_lshl_u32 v13, s5, v1, 10
	v_readlane_b32 s5, v254, 6
	v_and_b32_e32 v2, 15, v9
	v_lshlrev_b32_e32 v3, 2, v1
	s_add_u32 s2, s2, s5
	v_readlane_b32 s5, v254, 7
	v_lshrrev_b32_e32 v1, 4, v9
	v_bitop3_b32 v2, v3, v2, 12 bitop3:0x6c
	s_addc_u32 s3, s3, s5
	v_xor_b32_e32 v4, v1, v9
	v_ashrrev_i32_e32 v1, 31, v0
	v_lshlrev_b32_e32 v12, 3, v2
	v_lshl_add_u64 v[2:3], s[2:3], 0, v[0:1]
	v_lshlrev_b32_e32 v1, 4, v4
	v_and_b32_e32 v160, 0x70, v1
	v_add_u32_e32 v1, 64, v9
	v_ashrrev_i32_e32 v4, 3, v1
	v_lshrrev_b32_e32 v1, 4, v1
	v_ashrrev_i32_e32 v5, 31, v4
	v_xor_b32_e32 v1, v1, v9
	v_lshl_add_u64 v[4:5], s[2:3], 0, v[4:5]
	v_lshlrev_b64 v[4:5], 11, v[4:5]
	v_lshlrev_b32_e32 v1, 4, v1
	v_lshl_add_u64 v[4:5], s[92:93], 0, v[4:5]
	v_and_b32_e32 v6, 0x70, v1
	v_mov_b32_e32 v7, v161
	v_add_u32_e32 v1, 0x80, v9
	v_lshl_add_u64 v[4:5], v[4:5], 0, v[6:7]
	v_ashrrev_i32_e32 v6, 3, v1
	v_add_u32_e32 v1, 0xc0, v9
	v_lshlrev_b64 v[2:3], 11, v[2:3]
	v_readlane_b32 s5, v254, 5
	v_ashrrev_i32_e32 v7, 31, v6
	v_ashrrev_i32_e32 v8, 3, v1
	v_lshrrev_b32_e32 v1, 4, v1
	v_lshl_add_u64 v[2:3], s[92:93], 0, v[2:3]
	s_add_i32 s5, s5, 0
	v_lshl_add_u64 v[6:7], s[2:3], 0, v[6:7]
	v_xor_b32_e32 v1, v1, v9
	v_ashrrev_i32_e32 v9, 31, v8
	v_lshl_add_u64 v[2:3], v[2:3], 0, v[160:161]
	s_add_i32 s7, s5, 0x10000
	s_mov_b32 s8, m0
	s_mov_b32 m0, s7
	s_nop 0
	global_load_lds_dwordx4 v[2:3], off
	s_mov_b32 m0, s8
	v_lshlrev_b64 v[6:7], 11, v[6:7]
	v_lshl_add_u64 v[8:9], s[2:3], 0, v[8:9]
	s_add_i32 s7, s5, 0x10400
	s_mov_b32 s8, m0
	s_mov_b32 m0, s7
	s_nop 0
	global_load_lds_dwordx4 v[4:5], off
	s_mov_b32 m0, s8
	v_lshl_add_u64 v[6:7], s[92:93], 0, v[6:7]
	v_lshlrev_b64 v[8:9], 11, v[8:9]
	v_lshlrev_b32_e32 v1, 4, v1
	v_lshl_add_u64 v[6:7], v[6:7], 0, v[160:161]
	s_add_i32 s7, s5, 0x10800
	s_mov_b32 s8, m0
	s_mov_b32 m0, s7
	s_nop 0
	global_load_lds_dwordx4 v[6:7], off
	s_mov_b32 m0, s8
	v_lshl_add_u64 v[8:9], s[92:93], 0, v[8:9]
	v_and_b32_e32 v160, 0x70, v1
	v_lshl_add_u64 v[8:9], v[8:9], 0, v[160:161]
	s_add_i32 s7, s5, 0x10c00
	s_mov_b32 s8, m0
	s_mov_b32 m0, s7
	s_nop 0
	global_load_lds_dwordx4 v[8:9], off
	s_mov_b32 m0, s8
	v_lshl_add_u64 v[2:3], v[2:3], 0, s[38:39]
	s_add_i32 s7, s5, 0x11000
	s_mov_b32 s8, m0
	s_mov_b32 m0, s7
	s_nop 0
	global_load_lds_dwordx4 v[2:3], off
	s_mov_b32 m0, s8
	v_lshl_add_u64 v[2:3], v[4:5], 0, s[38:39]
	s_add_i32 s7, s5, 0x11400
	s_mov_b32 s8, m0
	s_mov_b32 m0, s7
	s_nop 0
	global_load_lds_dwordx4 v[2:3], off
	s_mov_b32 m0, s8
	v_lshl_add_u64 v[2:3], v[6:7], 0, s[38:39]
	s_add_i32 s7, s5, 0x11800
	s_mov_b32 s8, m0
	s_mov_b32 m0, s7
	s_nop 0
	global_load_lds_dwordx4 v[2:3], off
	s_mov_b32 m0, s8
	v_lshl_add_u64 v[2:3], v[8:9], 0, s[38:39]
	s_add_i32 s5, s5, 0x11c00
	s_mov_b32 s7, m0
	s_mov_b32 m0, s5
	s_nop 0
	global_load_lds_dwordx4 v[2:3], off
	s_mov_b32 m0, s7
	v_or3_b32 v160, v10, v11, s40
	v_lshl_add_u64 v[4:5], v[160:161], 1, s[66:67]
	s_mov_b32 s5, m0
	s_mov_b32 m0, s49
	s_nop 0
	global_load_lds_dwordx4 v[4:5], off
	s_mov_b32 m0, s5
	v_or3_b32 v2, v12, v13, s40
	v_lshl_add_u64 v[4:5], v[4:5], 0, s[38:39]
	s_mov_b32 s5, m0
	s_mov_b32 m0, s33
	s_nop 0
	global_load_lds_dwordx4 v[4:5], off
	s_mov_b32 m0, s5
	v_mov_b32_e32 v3, v161
	v_lshl_add_u64 v[4:5], v[2:3], 1, s[68:69]
	s_mov_b32 s5, m0
	s_mov_b32 m0, s54
	s_nop 0
	global_load_lds_dwordx4 v[4:5], off
	s_mov_b32 m0, s5
	v_add_u32_e32 v160, 0x8000, v2
	v_lshl_add_u64 v[2:3], v[160:161], 1, s[68:69]
	s_mov_b32 s5, m0
	s_mov_b32 m0, s47
	s_nop 0
	global_load_lds_dwordx4 v[2:3], off
	s_mov_b32 m0, s5
	s_lshl_b32 s4, s4, 22
	v_readlane_b32 s5, v255, 1
	s_waitcnt vmcnt(0)
	s_add_i32 s4, s5, s4
	v_lshlrev_b32_e32 v0, 10, v0
	v_or_b32_e32 v1, s40, v13
	v_add3_u32 v202, s4, v0, v10
	v_mov_b32_e32 v0, 0
	v_add_u32_e32 v201, v1, v12
	s_mov_b32 s4, 0
	s_mov_b32 s5, 0
	v_mov_b32_e32 v1, v0
	v_mov_b32_e32 v2, v0
	v_mov_b32_e32 v3, v0
	v_mov_b32_e32 v4, v0
	v_mov_b32_e32 v5, v0
	v_mov_b32_e32 v6, v0
	v_mov_b32_e32 v7, v0
	v_mov_b32_e32 v8, v0
	v_mov_b32_e32 v9, v0
	v_mov_b32_e32 v10, v0
	v_mov_b32_e32 v11, v0
	v_mov_b32_e32 v12, v0
	v_mov_b32_e32 v13, v0
	v_mov_b32_e32 v14, v0
	v_mov_b32_e32 v15, v0
	v_mov_b32_e32 v16, v0
	v_mov_b32_e32 v17, v0
	v_mov_b32_e32 v18, v0
	v_mov_b32_e32 v19, v0
	v_mov_b32_e32 v20, v0
	v_mov_b32_e32 v21, v0
	v_mov_b32_e32 v22, v0
	v_mov_b32_e32 v23, v0
	v_mov_b32_e32 v24, v0
	v_mov_b32_e32 v25, v0
	v_mov_b32_e32 v26, v0
	v_mov_b32_e32 v27, v0
	v_mov_b32_e32 v28, v0
	v_mov_b32_e32 v29, v0
	v_mov_b32_e32 v30, v0
	v_mov_b32_e32 v31, v0
	v_mov_b32_e32 v32, v0
	v_mov_b32_e32 v33, v0
	v_mov_b32_e32 v34, v0
	v_mov_b32_e32 v35, v0
	v_mov_b32_e32 v36, v0
	v_mov_b32_e32 v37, v0
	v_mov_b32_e32 v38, v0
	v_mov_b32_e32 v39, v0
	v_mov_b32_e32 v40, v0
	v_mov_b32_e32 v41, v0
	v_mov_b32_e32 v42, v0
	v_mov_b32_e32 v43, v0
	v_mov_b32_e32 v44, v0
	v_mov_b32_e32 v45, v0
	v_mov_b32_e32 v46, v0
	v_mov_b32_e32 v47, v0
	v_mov_b32_e32 v48, v0
	v_mov_b32_e32 v49, v0
	v_mov_b32_e32 v50, v0
	v_mov_b32_e32 v51, v0
	v_mov_b32_e32 v52, v0
	v_mov_b32_e32 v53, v0
	v_mov_b32_e32 v54, v0
	v_mov_b32_e32 v55, v0
	v_mov_b32_e32 v56, v0
	v_mov_b32_e32 v57, v0
	v_mov_b32_e32 v58, v0
	v_mov_b32_e32 v59, v0
	v_mov_b32_e32 v60, v0
	v_mov_b32_e32 v61, v0
	v_mov_b32_e32 v62, v0
	v_mov_b32_e32 v63, v0
	v_mov_b32_e32 v64, v0
	v_mov_b32_e32 v65, v0
	v_mov_b32_e32 v66, v0
	v_mov_b32_e32 v67, v0
	v_mov_b32_e32 v68, v0
	v_mov_b32_e32 v69, v0
	v_mov_b32_e32 v70, v0
	v_mov_b32_e32 v71, v0
	v_mov_b32_e32 v72, v0
	v_mov_b32_e32 v73, v0
	v_mov_b32_e32 v74, v0
	v_mov_b32_e32 v75, v0
	v_mov_b32_e32 v76, v0
	v_mov_b32_e32 v77, v0
	v_mov_b32_e32 v78, v0
	v_mov_b32_e32 v79, v0
	v_mov_b32_e32 v80, v0
	v_mov_b32_e32 v81, v0
	v_mov_b32_e32 v82, v0
	v_mov_b32_e32 v83, v0
	v_mov_b32_e32 v84, v0
	v_mov_b32_e32 v85, v0
	v_mov_b32_e32 v86, v0
	v_mov_b32_e32 v87, v0
	v_mov_b32_e32 v88, v0
	v_mov_b32_e32 v89, v0
	v_mov_b32_e32 v90, v0
	v_mov_b32_e32 v91, v0
	v_mov_b32_e32 v92, v0
	v_mov_b32_e32 v93, v0
	v_mov_b32_e32 v94, v0
	v_mov_b32_e32 v95, v0
	v_mov_b32_e32 v96, v0
	v_mov_b32_e32 v97, v0
	v_mov_b32_e32 v98, v0
	v_mov_b32_e32 v99, v0
	v_mov_b32_e32 v100, v0
	v_mov_b32_e32 v101, v0
	v_mov_b32_e32 v102, v0
	v_mov_b32_e32 v103, v0
	v_mov_b32_e32 v104, v0
	v_mov_b32_e32 v105, v0
	v_mov_b32_e32 v106, v0
	v_mov_b32_e32 v107, v0
	v_mov_b32_e32 v108, v0
	v_mov_b32_e32 v109, v0
	v_mov_b32_e32 v110, v0
	v_mov_b32_e32 v111, v0
	v_mov_b32_e32 v112, v0
	v_mov_b32_e32 v113, v0
	v_mov_b32_e32 v114, v0
	v_mov_b32_e32 v115, v0
	v_mov_b32_e32 v116, v0
	v_mov_b32_e32 v117, v0
	v_mov_b32_e32 v118, v0
	v_mov_b32_e32 v119, v0
	v_mov_b32_e32 v120, v0
	v_mov_b32_e32 v121, v0
	v_mov_b32_e32 v122, v0
	v_mov_b32_e32 v123, v0
	v_mov_b32_e32 v124, v0
	v_mov_b32_e32 v125, v0
	v_mov_b32_e32 v126, v0
	v_mov_b32_e32 v127, v0
	v_mov_b32_e32 v166, v0
	v_mov_b32_e32 v167, v0
	v_readlane_b32 s98, v253, 39
	s_cmpk_ge_u32 s98, 0x100
	s_cbranch_scc0 .Lattn_prio_skip_a
	s_setprio 0
